# strategy 6 on the 1.032x version: RWKV cumsum stage packs the wave's two adjacent timesteps into one ds_write_b32 for the transposed BKt/UV tiles (halves the 8-way bank-conflicted stores)
# baseline (speedup 1.0000x reference)
; DI bf16_t f2bf(float f) { return (bf16_t)(pack2(f, 0.f) & 0xFFFFu); }
; #define MFMA32(a, b, c) __builtin_amdgcn_mfma_f32_32x32x16_bf16((a), (b), (c), 0, 0, 0)
; __device__ __forceinline__ void rwkv_chunked(unsigned char* smem, CP p, int L, int b, int h) {
;     ...
;               const float kkv = k * k_k; const float ssq = wave_sum(kkv * kkv); const float kkn = kkv * rsqrtf(fmaxf(ssq, 1e-24f));
;               const float kx = k * (1.0f + (a - 1.0f) * k_a);
;               bon[i] = wave_sum(r * kx * r_k);
;               r_[i] = r; nk_[i] = kkn; ab_[i] = kkn * a; kx_[i] = kx; v_[i] = v; ew_[i] = ew; EW[t * 64 + c] = ew; } }
;         __syncthreads();
;         if (ch + 1 < SEQ / 16) RC_PREFETCH((ch + 1) * 16);
;         { float ev[16];
; #pragma unroll
;           for (int j = 0; j < 16; ++j) ev[j] = EW[j * 64 + c];
; #pragma unroll
;           for (int i = 0; i < 2; ++i) { const int t = wv * 2 + i; float cum = 0.f;
; #pragma unroll
;             for (int j = 0; j < 16; ++j) cum += (j <= t) ? ev[j] : 0.f;
;             const float Pt = __expf(-cum), Pm = __expf(-(cum - ew_[i])), iP = __expf(cum);
;             const float al = -nk_[i] * Pm, rh = r_[i] * Pt, be = ab_[i] * iP, ka = kx_[i] * iP;
;             AR[t * 72 + c] = f2bf(al); AR[(16 + t) * 72 + c] = f2bf(rh); BKr[t * 72 + c] = f2bf(be); BKr[(16 + t) * 72 + c] = f2bf(ka);
;             BKt[c * 40 + t] = f2bf(be); BKt[c * 40 + 16 + t] = f2bf(ka);
;             UV[c * 40 + 16 + t] = f2bf(v_[i]); VS[t * 64 + c] = v_[i];
;             if (t == 15) PC[c] = Pt; } }
;         __syncthreads();
;         f32x16 acc;
; #pragma unroll
;         for (int i = 0; i < 16; ++i) acc[i] = 0.f;
;         if (wv == 0) {
; #pragma unroll
;             for (int s = 0; s < 4; ++s) acc = MFMA32(*(const bf16x8*)(BKr + qi * 72 + 16 * s + 8 * hl), *(const bf16x8*)(AR + qi * 72 + 16 * s + 8 * hl), acc);
.LBB0_669:
	v_add_f32_e32 v13, v13, v14
	v_max_f32_e32 v13, 0x179abe15, v13
	v_add_f32_e32 v14, v32, v33
	v_rsq_f32_e32 v13, v13
	v_max_f32_e32 v14, 0x179abe15, v14
	v_rsq_f32_e32 v14, v14
	v_lshlrev_b32_e32 v11, 16, v11
	v_lshlrev_b32_e32 v44, 16, v0
	v_lshlrev_b32_e32 v3, 16, v3
	v_sub_f32_e32 v0, v11, v44
	v_mul_f32_e32 v13, v10, v13
	v_sub_f32_e32 v10, v44, v3
	v_fmac_f32_e32 v44, v64, v0
	v_fmac_f32_e32 v3, v64, v10
	v_mul_f32_e32 v45, v15, v14
	ds_read2st64_b32 v[10:11], v76 offset0:106 offset1:107
	ds_read2st64_b32 v[14:15], v76 offset0:108 offset1:109
	ds_read2st64_b32 v[32:33], v76 offset0:110 offset1:111
	ds_read2st64_b32 v[34:35], v76 offset0:112 offset1:113
	ds_read2st64_b32 v[36:37], v76 offset0:114 offset1:115
	ds_read2st64_b32 v[38:39], v76 offset0:116 offset1:117
	ds_read2st64_b32 v[40:41], v76 offset0:118 offset1:119
	ds_read2st64_b32 v[42:43], v76 offset0:120 offset1:121
	s_waitcnt lgkmcnt(7)
	v_add_f32_e32 v0, 0, v10
	v_cndmask_b32_e64 v0, v0, 0, s[58:59]
	v_cndmask_b32_e64 v10, v11, 0, s[60:61]
	v_add_f32_e32 v10, v0, v10
	s_waitcnt lgkmcnt(6)
	v_cndmask_b32_e64 v46, v14, 0, s[60:61]
	v_add_f32_e32 v10, v10, v46
	v_cndmask_b32_e64 v46, v15, 0, s[62:63]
	v_add_f32_e32 v10, v10, v46
	s_waitcnt lgkmcnt(5)
	v_cndmask_b32_e64 v46, v32, 0, s[62:63]
	v_add_f32_e32 v10, v10, v46
	v_cndmask_b32_e64 v46, v33, 0, s[54:55]
	v_add_f32_e32 v10, v10, v46
	s_waitcnt lgkmcnt(4)
	v_cndmask_b32_e64 v46, v34, 0, s[54:55]
	v_add_f32_e32 v10, v10, v46
	v_cndmask_b32_e64 v46, v35, 0, s[64:65]
	v_add_f32_e32 v10, v10, v46
	s_waitcnt lgkmcnt(3)
	v_cndmask_b32_e64 v46, v36, 0, s[64:65]
	v_add_f32_e32 v10, v10, v46
	v_cndmask_b32_e64 v46, v37, 0, s[66:67]
	v_add_f32_e32 v10, v10, v46
	s_waitcnt lgkmcnt(2)
	v_cndmask_b32_e64 v46, v38, 0, s[66:67]
	v_add_f32_e32 v10, v10, v46
	v_cndmask_b32_e64 v46, v39, 0, s[68:69]
	v_add_f32_e32 v10, v10, v46
	s_waitcnt lgkmcnt(1)
	v_cndmask_b32_e64 v46, v40, 0, s[68:69]
	v_add_f32_e32 v10, v10, v46
	v_cndmask_b32_e64 v46, v41, 0, s[70:71]
	v_add_f32_e32 v10, v10, v46
	s_waitcnt lgkmcnt(0)
	v_cndmask_b32_e64 v46, v42, 0, s[70:71]
	v_add_f32_e32 v10, v10, v46
	v_cndmask_b32_e64 v46, v43, 0, s[72:73]
	v_add_f32_e32 v10, v10, v46
	v_mov_b32_e32 v114, v10
	v_sub_f32_e32 v5, v10, v5
	v_mul_f32_e32 v46, 0xbfb8aa3b, v10
	v_mul_f32_e32 v5, 0xbfb8aa3b, v5
	v_exp_f32_e32 v46, v46
	v_exp_f32_e32 v5, v5
	v_mul_f32_e32 v10, 0x3fb8aa3b, v10
	v_exp_f32_e32 v10, v10
	v_mul_f32_e32 v9, v9, v13
	v_mul_f32_e64 v5, v5, -v13
	v_mul_f32_e32 v4, v4, v46
	v_mul_f32_e32 v9, v9, v10
	v_mul_f32_e32 v7, v7, v10
	v_cvt_pk_bf16_f32 v5, v5, s0
	v_cvt_pk_bf16_f32 v4, v4, s0
	ds_write_b16 v92, v5 offset:9216
	ds_write_b16 v92, v4 offset:11520
	v_cvt_pk_bf16_f32 v4, v9, s0
	v_cvt_pk_bf16_f32 v5, v7, s0
	ds_write_b16 v92, v4 offset:31232
	ds_write_b16 v92, v5 offset:33536
	s_nop 0
	s_nop 0
	v_add_f32_e32 v5, v114, v6
	v_sub_f32_e32 v6, v5, v6
	v_mul_f32_e32 v0, 0xbfb8aa3b, v5
	v_mul_f32_e32 v6, 0xbfb8aa3b, v6
	v_exp_f32_e32 v0, v0
	v_exp_f32_e32 v6, v6
	v_mul_f32_e32 v5, 0x3fb8aa3b, v5
	v_exp_f32_e32 v5, v5
	v_cvt_pk_bf16_f32 v4, v44, s0
	s_nop 0
	v_add_u32_e32 v4, v77, v90
	v_mul_f32_e32 v12, v12, v45
	ds_write_b32 v4, v44 offset:61312
	v_mul_f32_e64 v4, v6, -v45
	v_mul_f32_e32 v2, v2, v0
	v_mul_f32_e32 v6, v12, v5
	v_mul_f32_e32 v5, v8, v5
	v_cvt_pk_bf16_f32 v4, v4, s0
	v_cvt_pk_bf16_f32 v2, v2, s0
	ds_write_b16 v96, v4 offset:9216
	ds_write_b16 v96, v2 offset:11520
	v_cvt_pk_bf16_f32 v2, v6, s0
	v_cvt_pk_bf16_f32 v4, v5, s0
	v_cvt_pk_bf16_f32 v115, v9, v6
	v_cvt_pk_bf16_f32 v116, v7, v5
	ds_write_b16 v96, v2 offset:31232
	ds_write_b16 v96, v4 offset:33536
	ds_write_b32 v94, v115 offset:13824
	ds_write_b32 v95, v116 offset:13856
	v_cvt_pk_bf16_f32 v117, v44, v3
	ds_write_b32 v95, v117 offset:18976
	v_add_u32_e32 v2, v77, v98
	ds_write_b32 v2, v3 offset:61312
	s_and_saveexec_b64 s[16:17], s[8:9]
	ds_write_b32 v77, v0 offset:65408
	s_or_b64 exec, exec, s[16:17]
	s_waitcnt lgkmcnt(0)
	s_barrier
	s_and_saveexec_b64 s[16:17], s[48:49]
	s_xor_b64 vcc, exec, s[16:17]
	s_cbranch_execz .LBB0_675
	v_mov_b32_e32 v14, v1
	v_mov_b32_e32 v15, v1
	v_mov_b32_e32 v0, v1
	v_mov_b32_e32 v2, v1
	v_mov_b32_e32 v3, v1
	v_mov_b32_e32 v4, v1
	v_mov_b32_e32 v5, v1
	v_mov_b32_e32 v6, v1
	v_mov_b32_e32 v7, v1
	v_mov_b32_e32 v8, v1
	v_mov_b32_e32 v9, v1
	v_mov_b32_e32 v10, v1
	v_mov_b32_e32 v11, v1
	v_mov_b32_e32 v12, v1
	v_mov_b32_e32 v13, v1
	v_mov_b64_e32 v[46:47], v[14:15]
	v_mov_b64_e32 v[44:45], v[12:13]
	v_mov_b64_e32 v[42:43], v[10:11]
	v_mov_b64_e32 v[40:41], v[8:9]
	v_mov_b64_e32 v[38:39], v[6:7]
	v_mov_b64_e32 v[36:37], v[4:5]
	v_mov_b64_e32 v[34:35], v[2:3]
	v_mov_b64_e32 v[32:33], v[0:1]
	s_and_saveexec_b64 s[16:17], s[54:55]
	s_cbranch_execz .LBB0_674
	ds_read_b128 v[2:5], v79
	ds_read_b128 v[6:9], v80 offset:9216
	ds_read_b128 v[114:117], v79 offset:32
	ds_read_b128 v[118:121], v80 offset:9248
	ds_read_b128 v[122:125], v79 offset:64
	ds_read_b128 v[126:129], v80 offset:9280
	ds_read_b128 v[130:133], v79 offset:96
	ds_read_b128 v[134:137], v80 offset:9312
	s_waitcnt lgkmcnt(6)
	v_mfma_f32_32x32x16_bf16 v[32:47], v[2:5], v[6:9], 0
	s_waitcnt lgkmcnt(4)
	v_mfma_f32_32x32x16_bf16 v[32:47], v[114:117], v[118:121], v[32:47]
	s_waitcnt lgkmcnt(2)
	v_mfma_f32_32x32x16_bf16 v[32:47], v[122:125], v[126:129], v[32:47]
	s_waitcnt lgkmcnt(0)
	v_mfma_f32_32x32x16_bf16 v[32:47], v[130:133], v[134:137], v[32:47]
